# adds: follower half (waves 0-3) executes s_sleep 2 at the start of each prompt-attention tile compute so the priority half's K-fragment LDS reads are served first
# baseline (speedup 1.0000x reference)
; #define LAS __attribute__((address_space(3)))
; __device__ __forceinline__ int crow(int r, int hi) { return (r & 3) + 8 * (r >> 2) + 4 * hi; }
; template <int DQK, int DV, bool HAS_BIAS>
; __device__ __forceinline__ void attn_tile(AttnState<DQK, DV>& st, const LAS unsigned char* Kt, const LAS unsigned char* Vt, int bias_mode, const LAS float* tab, int rel0, int nkeys, bool first, LAS float* wsf, int lane) {
;     ...
;     const LAS unsigned char* kp = Kt + q * PK + hi * 16;
;     bf16x8 ka[KS], kb[KS];
; #pragma unroll
;     for (int ks = 0; ks < KS; ++ks) { ka[ks] = *(const LAS bf16x8*)(kp + ks * 32); kb[ks] = *(const LAS bf16x8*)(kp + 32 * PK + ks * 32); }
;     if (HAS_BIAS && bias_mode == 2) {
;         asm volatile("" ::: "memory");
; #pragma unroll
;         for (int r = 0; r < 16; ++r) {
;             const int k = crow(r, hi);
;             const int i0 = min(max(rel0 + k + 128, 0), 191), i1 = min(max(rel0 + k + 160, 0), 191);
;             p0[r] = tab[i0] + st.negm[r]; p1[r] = tab[i1] + st.negm[r];
;         }
;         p0 = __builtin_amdgcn_mfma_f32_32x32x16_bf16(ka[0], st.qf[0], p0, 0, 0, 0);
;         p1 = __builtin_amdgcn_mfma_f32_32x32x16_bf16(kb[0], st.qf[0], p1, 0, 0, 0);
;     } else {
;         p0 = __builtin_amdgcn_mfma_f32_32x32x16_bf16(ka[0], st.qf[0], st.negm, 0, 0, 0);
;         p1 = __builtin_amdgcn_mfma_f32_32x32x16_bf16(kb[0], st.qf[0], st.negm, 0, 0, 0);
.LBB0_522:
	s_cmp_gt_i32 s59, s7
	s_cbranch_scc1 .LBB0_536
	v_readlane_b32 s98, v247, 43
	s_cmp_ge_u32 s98, 4
	s_cbranch_scc1 .Lskew_a
	s_sleep 2
.Lskew_a:
	ds_read_b128 v[180:183], v221 offset:8192
	ds_read_b128 v[160:163], v221 offset:8224
	ds_read_b128 v[176:179], v221 offset:12800
	ds_read_b128 v[164:167], v221 offset:12832
	ds_read_b128 v[156:159], v221 offset:8256
	ds_read_b128 v[152:155], v221 offset:8288
	ds_read_b128 v[172:175], v221 offset:12864
	ds_read_b128 v[168:171], v221 offset:12896
	s_add_i32 s2, s92, s58
	s_add_i32 s2, s2, 63
	s_cmpk_lt_i32 s2, 0xff81
	s_mov_b64 s[2:3], -1
	s_cbranch_scc0 .LBB0_525
	s_waitcnt vmcnt(6) lgkmcnt(7)
	v_mfma_f32_32x32x16_bf16 v[80:95], v[180:183], v[112:115], v[64:79]
	s_mov_b64 s[2:3], 0
	s_waitcnt lgkmcnt(5)
	v_mfma_f32_32x32x16_bf16 v[96:111], v[176:179], v[112:115], v[64:79]

.LBB0_543:
	v_readlane_b32 s98, v247, 43
	s_cmp_ge_u32 s98, 4
	s_cbranch_scc1 .Lskew_b
	s_sleep 2
